# MLA attention: LDS K/V fragment reads of each MFMA cluster issued one cluster earlier into spare VGPRs
# baseline (speedup 1.0000x reference)
.LBB0_559:
	s_and_b32 s5, s4, 0x80
	v_or_b32_e32 v142, s5, v125
	v_mad_u32_u24 v143, v142, s12, v0
	ds_read_b128 v[78:81], v143
	ds_read_b128 v[82:85], v143 offset:64
	ds_read_b128 v[86:89], v143 offset:128
	ds_read_b128 v[94:97], v143 offset:3328
	ds_read_b128 v[98:101], v143 offset:3392
	ds_read_b128 v[144:147], v143 offset:3456
	ds_read_b128 v[224:227], v143 offset:6656
	ds_read_b128 v[228:231], v143 offset:6720
	ds_read_b128 v[232:235], v143 offset:6784
	ds_read_b128 v[236:239], v143 offset:9984
	ds_read_b128 v[240:243], v143 offset:10048
	ds_read_b128 v[244:247], v143 offset:10112
	s_setprio 1
	s_waitcnt lgkmcnt(11)
	v_mfma_f32_16x16x32_bf16 v[90:93], v[78:81], v[2:5], 0
	v_mfma_f32_16x16x32_bf16 v[78:81], v[78:81], v[26:29], 0
	s_waitcnt lgkmcnt(10)
	v_mfma_f32_16x16x32_bf16 v[90:93], v[82:85], v[6:9], v[90:93]
	v_mfma_f32_16x16x32_bf16 v[78:81], v[82:85], v[30:33], v[78:81]
	s_waitcnt lgkmcnt(9)
	v_mfma_f32_16x16x32_bf16 v[106:109], v[86:89], v[38:41], v[90:93]
	v_mfma_f32_16x16x32_bf16 v[90:93], v[86:89], v[42:45], v[78:81]
	s_waitcnt lgkmcnt(8)
	v_mfma_f32_16x16x32_bf16 v[78:81], v[94:97], v[2:5], 0
	v_mfma_f32_16x16x32_bf16 v[82:85], v[94:97], v[26:29], 0
	s_waitcnt lgkmcnt(7)
	v_mfma_f32_16x16x32_bf16 v[78:81], v[98:101], v[6:9], v[78:81]
	v_mfma_f32_16x16x32_bf16 v[82:85], v[98:101], v[30:33], v[82:85]
	s_waitcnt lgkmcnt(6)
	v_mfma_f32_16x16x32_bf16 v[102:105], v[144:147], v[38:41], v[78:81]
	v_mfma_f32_16x16x32_bf16 v[82:85], v[144:147], v[42:45], v[82:85]
	s_setprio 0
	s_nop 2
	s_setprio 1
	s_waitcnt lgkmcnt(5)
	v_mfma_f32_16x16x32_bf16 v[98:101], v[224:227], v[2:5], 0
	v_mfma_f32_16x16x32_bf16 v[78:81], v[224:227], v[26:29], 0
	s_waitcnt lgkmcnt(4)
	v_mfma_f32_16x16x32_bf16 v[98:101], v[228:231], v[6:9], v[98:101]
	v_mfma_f32_16x16x32_bf16 v[78:81], v[228:231], v[30:33], v[78:81]
	s_waitcnt lgkmcnt(3)
	v_mfma_f32_16x16x32_bf16 v[98:101], v[232:235], v[38:41], v[98:101]
	v_mfma_f32_16x16x32_bf16 v[86:89], v[232:235], v[42:45], v[78:81]
	s_waitcnt lgkmcnt(2)
	v_mfma_f32_16x16x32_bf16 v[78:81], v[236:239], v[2:5], 0
	v_mfma_f32_16x16x32_bf16 v[94:97], v[236:239], v[26:29], 0
	s_waitcnt lgkmcnt(1)
	v_mfma_f32_16x16x32_bf16 v[78:81], v[240:243], v[6:9], v[78:81]
	v_mfma_f32_16x16x32_bf16 v[144:147], v[240:243], v[30:33], v[94:97]
	s_waitcnt lgkmcnt(0)
	v_mfma_f32_16x16x32_bf16 v[94:97], v[244:247], v[38:41], v[78:81]
	v_mfma_f32_16x16x32_bf16 v[78:81], v[244:247], v[42:45], v[144:147]
	s_setprio 0
	v_max3_f32 v143, v106, s18, v107
	v_max3_f32 v143, v143, v108, v109
	v_max3_f32 v143, v143, v102, v103
	v_max3_f32 v143, v143, v104, v105
	v_max3_f32 v143, v143, v98, v99
	v_max3_f32 v143, v143, v100, v101
	v_max3_f32 v143, v143, v94, v95
	v_max3_f32 v143, v143, v96, v97
	v_mul_f32_e32 v143, 0x3e16c740, v143
	ds_bpermute_b32 v144, v124, v143
	s_waitcnt lgkmcnt(0)
	v_max_f32_e32 v144, v144, v144
	v_max_f32_e32 v143, v143, v144
	ds_bpermute_b32 v144, v129, v143
	s_waitcnt lgkmcnt(0)
	v_max_f32_e32 v144, v144, v144
	v_max_f32_e32 v143, v143, v144
	v_add_f32_e32 v144, 0x41000000, v139
	v_cmp_gt_f32_e32 vcc, v143, v144
	s_cbranch_vccz .LBB0_561
	v_max_f32_e32 v143, v143, v143
	v_max_f32_e32 v144, v139, v139
	v_max_f32_e32 v143, v144, v143
	v_sub_f32_e32 v139, v139, v143
	v_exp_f32_e32 v144, v139
	v_mov_b32_e32 v139, v143
	v_mul_f32_e32 v141, v141, v144
	v_pk_mul_f32 v[76:77], v[76:77], v[144:145] op_sel_hi:[1,0]
	v_pk_mul_f32 v[74:75], v[74:75], v[144:145] op_sel_hi:[1,0]
	v_pk_mul_f32 v[72:73], v[72:73], v[144:145] op_sel_hi:[1,0]
	v_pk_mul_f32 v[70:71], v[70:71], v[144:145] op_sel_hi:[1,0]
	v_pk_mul_f32 v[68:69], v[68:69], v[144:145] op_sel_hi:[1,0]
	v_pk_mul_f32 v[66:67], v[66:67], v[144:145] op_sel_hi:[1,0]
	v_pk_mul_f32 v[64:65], v[64:65], v[144:145] op_sel_hi:[1,0]
	v_pk_mul_f32 v[62:63], v[62:63], v[144:145] op_sel_hi:[1,0]

.LBB0_563:
	v_fma_f32 v106, v106, s21, -v139
	v_exp_f32_e32 v106, v106
	v_fma_f32 v107, v107, s21, -v139
	v_exp_f32_e32 v107, v107
	v_fma_f32 v108, v108, s21, -v139
	v_exp_f32_e32 v108, v108
	v_fma_f32 v109, v109, s21, -v139
	v_exp_f32_e32 v109, v109
	v_fma_f32 v102, v102, s21, -v139
	v_mul_u32_u24_e32 v160, 0xd0, v142
	v_add_f32_e32 v142, 0, v106
	v_exp_f32_e32 v102, v102
	v_fma_f32 v103, v103, s21, -v139
	v_add_f32_e32 v142, v107, v142
	v_exp_f32_e32 v103, v103
	v_fma_f32 v104, v104, s21, -v139
	v_add_f32_e32 v142, v108, v142
	v_exp_f32_e32 v104, v104
	v_fma_f32 v105, v105, s21, -v139
	v_add_f32_e32 v142, v109, v142
	v_exp_f32_e32 v105, v105
	v_fma_f32 v98, v98, s21, -v139
	v_cvt_pk_bf16_f32 v106, v106, v107
	v_cvt_pk_bf16_f32 v107, v108, v109
	v_add_f32_e32 v108, v102, v142
	v_exp_f32_e32 v98, v98
	v_fma_f32 v99, v99, s21, -v139
	v_add_f32_e32 v108, v103, v108
	v_exp_f32_e32 v99, v99
	v_fma_f32 v100, v100, s21, -v139
	v_add_f32_e32 v108, v104, v108
	v_exp_f32_e32 v100, v100
	v_fma_f32 v101, v101, s21, -v139
	v_add_f32_e32 v142, v105, v108
	v_exp_f32_e32 v101, v101
	v_fma_f32 v94, v94, s21, -v139
	v_cvt_pk_bf16_f32 v108, v102, v103
	v_add_f32_e32 v102, v98, v142
	v_exp_f32_e32 v94, v94
	v_fma_f32 v95, v95, s21, -v139
	v_add_f32_e32 v102, v99, v102
	v_exp_f32_e32 v95, v95
	v_fma_f32 v96, v96, s21, -v139
	v_add_f32_e32 v102, v100, v102
	v_exp_f32_e32 v96, v96
	v_fma_f32 v97, v97, s21, -v139
	v_add_f32_e32 v102, v101, v102
	v_exp_f32_e32 v97, v97
	v_cvt_pk_bf16_f32 v98, v98, v99
	v_cvt_pk_bf16_f32 v99, v100, v101
	v_add_f32_e32 v100, v94, v102
	v_add_f32_e32 v100, v95, v100
	v_add_f32_e32 v100, v96, v100
	v_fma_f32 v90, v90, s21, -v138
	v_fma_f32 v86, v86, s21, -v138
	v_fma_f32 v78, v78, s21, -v138
	v_add_f32_e32 v102, v97, v100
	v_cvt_pk_bf16_f32 v100, v94, v95
	v_or_b32_e32 v94, s5, v132
	v_exp_f32_e32 v144, v90
	v_fma_f32 v90, v91, s21, -v138
	v_exp_f32_e32 v159, v86
	v_fma_f32 v86, v87, s21, -v138
	v_exp_f32_e32 v154, v78
	v_fma_f32 v78, v79, s21, -v138
	v_exp_f32_e32 v145, v90
	v_fma_f32 v90, v92, s21, -v138
	v_exp_f32_e32 v146, v86
	v_fma_f32 v86, v88, s21, -v138
	v_exp_f32_e32 v151, v78
	v_fma_f32 v78, v80, s21, -v138
	v_mul_u32_u24_e32 v143, 0x48, v94
	v_exp_f32_e32 v147, v90
	v_fma_f32 v90, v93, s21, -v138
	v_exp_f32_e32 v148, v86
	v_fma_f32 v86, v89, s21, -v138
	v_exp_f32_e32 v152, v78
	v_fma_f32 v78, v81, s21, -v138
	v_lshl_add_u32 v142, v143, 1, v130
	v_cvt_pk_bf16_f32 v101, v96, v97
	v_exp_f32_e32 v149, v90
	v_exp_f32_e32 v150, v86
	v_exp_f32_e32 v155, v78
	ds_read_b64_tr_b16 v[80:81], v142 offset:55552
	ds_read_b64_tr_b16 v[78:79], v142 offset:53248
	ds_read_b64_tr_b16 v[88:89], v142 offset:55584
	ds_read_b64_tr_b16 v[86:87], v142 offset:53280
	ds_read_b64_tr_b16 v[90:91], v142 offset:57856
	ds_read_b64_tr_b16 v[92:93], v142 offset:60160
	ds_read_b64_tr_b16 v[96:97], v142 offset:60192
	ds_read_b64_tr_b16 v[94:95], v142 offset:57888
	ds_read_b64_tr_b16 v[226:227], v142 offset:55616
	ds_read_b64_tr_b16 v[224:225], v142 offset:53312
	ds_read_b64_tr_b16 v[230:231], v142 offset:55648
	ds_read_b64_tr_b16 v[228:229], v142 offset:53344
	ds_read_b64_tr_b16 v[232:233], v142 offset:57920
	ds_read_b64_tr_b16 v[234:235], v142 offset:60224
	ds_read_b64_tr_b16 v[238:239], v142 offset:60256
	ds_read_b64_tr_b16 v[236:237], v142 offset:57952
	v_fma_f32 v82, v82, s21, -v138
	v_exp_f32_e32 v153, v82
	v_fma_f32 v82, v83, s21, -v138
	v_exp_f32_e32 v156, v82
	v_fma_f32 v82, v84, s21, -v138
	v_exp_f32_e32 v157, v82
	v_fma_f32 v82, v85, s21, -v138
	v_exp_f32_e32 v158, v82
	v_cvt_pk_bf16_f32 v109, v104, v105
	v_add_f32_e32 v141, v141, v102
	v_cvt_pk_bf16_f32 v82, v144, v145
	v_cvt_pk_bf16_f32 v83, v147, v149
	v_cvt_pk_bf16_f32 v84, v153, v156
	v_cvt_pk_bf16_f32 v85, v157, v158
	v_cvt_pk_bf16_f32 v102, v159, v146
	v_cvt_pk_bf16_f32 v103, v148, v150
	v_cvt_pk_bf16_f32 v104, v154, v151
	v_cvt_pk_bf16_f32 v105, v152, v155
	s_setprio 1
	s_waitcnt lgkmcnt(14)
	v_mfma_f32_16x16x32_bf16 v[74:77], v[78:81], v[106:109], v[74:77]
	v_mfma_f32_16x16x32_bf16 v[58:61], v[78:81], v[82:85], v[58:61]
	s_waitcnt lgkmcnt(12)
	v_mfma_f32_16x16x32_bf16 v[70:73], v[86:89], v[106:109], v[70:73]
	v_mfma_f32_16x16x32_bf16 v[78:81], v[86:89], v[82:85], v[54:57]
	s_waitcnt lgkmcnt(10)
	v_mfma_f32_16x16x32_bf16 v[74:77], v[90:93], v[98:101], v[74:77]
	v_mfma_f32_16x16x32_bf16 v[58:61], v[90:93], v[102:105], v[58:61]
	s_waitcnt lgkmcnt(8)
	v_mfma_f32_16x16x32_bf16 v[54:57], v[94:97], v[98:101], v[70:73]
	v_mfma_f32_16x16x32_bf16 v[70:73], v[94:97], v[102:105], v[78:81]
	s_setprio 0
	s_nop 1
	v_add_u32_e32 v160, v0, v160
	ds_read_b128 v[240:243], v160 offset:13312
	ds_read_b128 v[244:247], v160 offset:13376
	ds_read_b128 v[86:89], v160 offset:13440
	ds_read_b128 v[94:97], v160 offset:16640
	ds_read_b128 v[200:203], v160 offset:16704
	ds_read_b128 v[182:185], v160 offset:16768
	s_setprio 1
	s_waitcnt lgkmcnt(12)
	v_mfma_f32_16x16x32_bf16 v[66:69], v[224:227], v[106:109], v[66:69]
	v_mfma_f32_16x16x32_bf16 v[78:81], v[224:227], v[82:85], v[50:53]
	s_waitcnt lgkmcnt(8)
	v_mfma_f32_16x16x32_bf16 v[50:53], v[232:235], v[98:101], v[66:69]
	v_mfma_f32_16x16x32_bf16 v[66:69], v[232:235], v[102:105], v[78:81]
	v_mfma_f32_16x16x32_bf16 v[62:65], v[228:231], v[106:109], v[62:65]
	v_mfma_f32_16x16x32_bf16 v[78:81], v[228:231], v[82:85], v[46:49]
	s_waitcnt lgkmcnt(6)
	v_mfma_f32_16x16x32_bf16 v[46:49], v[236:239], v[98:101], v[62:65]
	v_mfma_f32_16x16x32_bf16 v[62:65], v[236:239], v[102:105], v[78:81]
	s_setprio 0
	s_nop 2
	ds_read_b128 v[224:227], v160 offset:19968
	ds_read_b128 v[228:231], v160 offset:20032
	ds_read_b128 v[232:235], v160 offset:20096
	ds_read_b128 v[164:167], v160 offset:23296
	ds_read_b128 v[168:171], v160 offset:23360
	ds_read_b128 v[172:175], v160 offset:23424
	s_setprio 1
	s_waitcnt lgkmcnt(11)
	v_mfma_f32_16x16x32_bf16 v[90:93], v[240:243], v[2:5], 0
	v_mfma_f32_16x16x32_bf16 v[78:81], v[240:243], v[26:29], 0
	s_waitcnt lgkmcnt(10)
	v_mfma_f32_16x16x32_bf16 v[90:93], v[244:247], v[6:9], v[90:93]
	v_mfma_f32_16x16x32_bf16 v[78:81], v[244:247], v[30:33], v[78:81]
	s_waitcnt lgkmcnt(9)
	v_mfma_f32_16x16x32_bf16 v[106:109], v[86:89], v[38:41], v[90:93]
	v_mfma_f32_16x16x32_bf16 v[90:93], v[86:89], v[42:45], v[78:81]
	s_waitcnt lgkmcnt(8)
	v_mfma_f32_16x16x32_bf16 v[78:81], v[94:97], v[2:5], 0
	v_mfma_f32_16x16x32_bf16 v[82:85], v[94:97], v[26:29], 0
	s_waitcnt lgkmcnt(7)
	v_mfma_f32_16x16x32_bf16 v[78:81], v[200:203], v[6:9], v[78:81]
	v_mfma_f32_16x16x32_bf16 v[82:85], v[200:203], v[30:33], v[82:85]
	s_waitcnt lgkmcnt(6)
	v_mfma_f32_16x16x32_bf16 v[98:101], v[182:185], v[38:41], v[78:81]
	v_mfma_f32_16x16x32_bf16 v[82:85], v[182:185], v[42:45], v[82:85]
	s_setprio 0
	s_nop 2
	s_setprio 1
	s_waitcnt lgkmcnt(5)
	v_mfma_f32_16x16x32_bf16 v[102:105], v[224:227], v[2:5], 0
	v_mfma_f32_16x16x32_bf16 v[78:81], v[224:227], v[26:29], 0
	s_waitcnt lgkmcnt(4)
	v_mfma_f32_16x16x32_bf16 v[102:105], v[228:231], v[6:9], v[102:105]
	v_mfma_f32_16x16x32_bf16 v[78:81], v[228:231], v[30:33], v[78:81]
	s_waitcnt lgkmcnt(3)
	v_mfma_f32_16x16x32_bf16 v[102:105], v[232:235], v[38:41], v[102:105]
	v_mfma_f32_16x16x32_bf16 v[86:89], v[232:235], v[42:45], v[78:81]
	s_waitcnt lgkmcnt(2)
	v_mfma_f32_16x16x32_bf16 v[78:81], v[164:167], v[2:5], 0
	v_mfma_f32_16x16x32_bf16 v[94:97], v[164:167], v[26:29], 0
	s_waitcnt lgkmcnt(1)
	v_mfma_f32_16x16x32_bf16 v[78:81], v[168:171], v[6:9], v[78:81]
	v_mfma_f32_16x16x32_bf16 v[164:167], v[168:171], v[30:33], v[94:97]
	s_waitcnt lgkmcnt(0)
	v_mfma_f32_16x16x32_bf16 v[94:97], v[172:175], v[38:41], v[78:81]
	v_mfma_f32_16x16x32_bf16 v[78:81], v[172:175], v[42:45], v[164:167]
	s_setprio 0
	v_max3_f32 v160, v106, s18, v107
	v_max3_f32 v160, v160, v108, v109
	v_max3_f32 v160, v160, v98, v99
	v_max3_f32 v160, v160, v100, v101
	v_max3_f32 v160, v160, v102, v103
	v_max3_f32 v160, v160, v104, v105
	v_max3_f32 v160, v160, v94, v95
	v_max3_f32 v160, v160, v96, v97
	v_mul_f32_e32 v160, 0x3e16c740, v160
	ds_bpermute_b32 v161, v124, v160
	s_waitcnt lgkmcnt(0)
	v_max_f32_e32 v161, v161, v161
	v_max_f32_e32 v160, v160, v161
	ds_bpermute_b32 v161, v129, v160
	s_waitcnt lgkmcnt(0)
	v_max_f32_e32 v161, v161, v161
	v_max_f32_e32 v160, v160, v161
	v_add_f32_e32 v161, 0x41000000, v139
	v_cmp_gt_f32_e32 vcc, v160, v161
	s_cbranch_vccz .LBB0_565
	v_max_f32_e32 v160, v160, v160
	v_max_f32_e32 v161, v139, v139
	v_max_f32_e32 v161, v161, v160
	v_sub_f32_e32 v139, v139, v161
	v_exp_f32_e32 v160, v139
	v_mov_b32_e32 v139, v161
	v_mul_f32_e32 v141, v141, v160
	v_pk_mul_f32 v[76:77], v[76:77], v[160:161] op_sel_hi:[1,0]
	v_pk_mul_f32 v[74:75], v[74:75], v[160:161] op_sel_hi:[1,0]
	v_pk_mul_f32 v[56:57], v[56:57], v[160:161] op_sel_hi:[1,0]
	v_pk_mul_f32 v[54:55], v[54:55], v[160:161] op_sel_hi:[1,0]
	v_pk_mul_f32 v[52:53], v[52:53], v[160:161] op_sel_hi:[1,0]
	v_pk_mul_f32 v[50:51], v[50:51], v[160:161] op_sel_hi:[1,0]
	v_pk_mul_f32 v[48:49], v[48:49], v[160:161] op_sel_hi:[1,0]
	v_pk_mul_f32 v[46:47], v[46:47], v[160:161] op_sel_hi:[1,0]
	v_xor_b32_e32 v160, 0x80000000, v161
	s_branch .LBB0_566

.LBB0_569:
	v_lshl_add_u32 v180, v143, 1, v210
	v_fmamk_f32 v106, v106, 0x3e16c740, v160
	v_fmamk_f32 v107, v107, 0x3e16c740, v160
	v_fmamk_f32 v108, v108, 0x3e16c740, v160
	v_fmamk_f32 v109, v109, 0x3e16c740, v160
	v_fmamk_f32 v98, v98, 0x3e16c740, v160
	v_fmamk_f32 v99, v99, 0x3e16c740, v160
	v_fmamk_f32 v100, v100, 0x3e16c740, v160
	v_fmamk_f32 v101, v101, 0x3e16c740, v160
	v_fmamk_f32 v102, v102, 0x3e16c740, v160
	v_fmamk_f32 v103, v103, 0x3e16c740, v160
	v_fmamk_f32 v104, v104, 0x3e16c740, v160
	v_fmamk_f32 v105, v105, 0x3e16c740, v160
	v_fmamk_f32 v94, v94, 0x3e16c740, v160
	v_fmamk_f32 v95, v95, 0x3e16c740, v160
	v_fmamk_f32 v96, v96, 0x3e16c740, v160
	v_fmac_f32_e32 v160, 0x3e16c740, v97
	v_fmamk_f32 v90, v90, 0x3e16c740, v144
	v_fmamk_f32 v91, v91, 0x3e16c740, v144
	v_fmamk_f32 v92, v92, 0x3e16c740, v144
	v_fmamk_f32 v93, v93, 0x3e16c740, v144
	v_fmamk_f32 v82, v82, 0x3e16c740, v144
	v_fmamk_f32 v83, v83, 0x3e16c740, v144
	v_fmamk_f32 v84, v84, 0x3e16c740, v144
	v_fmamk_f32 v85, v85, 0x3e16c740, v144
	v_fmamk_f32 v86, v86, 0x3e16c740, v144
	v_fmamk_f32 v87, v87, 0x3e16c740, v144
	v_fmamk_f32 v88, v88, 0x3e16c740, v144
	v_fmamk_f32 v89, v89, 0x3e16c740, v144
	v_fmamk_f32 v78, v78, 0x3e16c740, v144
	v_fmamk_f32 v79, v79, 0x3e16c740, v144
	v_fmamk_f32 v80, v80, 0x3e16c740, v144
	v_fmac_f32_e32 v144, 0x3e16c740, v81
	v_add_u32_e32 v143, v133, v180
	v_exp_f32_e32 v97, v160
	v_exp_f32_e32 v81, v144
	ds_read_b64_tr_b16 v[160:161], v142 offset:64768
	ds_read_b64_tr_b16 v[158:159], v142 offset:62464
	ds_read_b64_tr_b16 v[166:167], v142 offset:64800
	ds_read_b64_tr_b16 v[164:165], v142 offset:62496
	v_add_u32_e32 v144, v134, v180
	ds_read_b64_tr_b16 v[168:169], v143
	ds_read_b64_tr_b16 v[170:171], v143 offset:2304
	ds_read_b64_tr_b16 v[172:173], v144
	ds_read_b64_tr_b16 v[174:175], v144 offset:2304
	v_add_u32_e32 v186, v135, v180
	v_add_u32_e32 v187, v136, v180
	ds_read_b64_tr_b16 v[226:227], v142 offset:64832
	ds_read_b64_tr_b16 v[224:225], v142 offset:62528
	ds_read_b64_tr_b16 v[230:231], v142 offset:64864
	ds_read_b64_tr_b16 v[228:229], v142 offset:62560
	ds_read_b64_tr_b16 v[232:233], v186
	ds_read_b64_tr_b16 v[234:235], v186 offset:2304
	ds_read_b64_tr_b16 v[236:237], v187
	ds_read_b64_tr_b16 v[238:239], v187 offset:2304
	v_exp_f32_e32 v106, v106
	v_exp_f32_e32 v107, v107
	v_exp_f32_e32 v108, v108
	v_exp_f32_e32 v109, v109
	v_exp_f32_e32 v98, v98
	v_exp_f32_e32 v99, v99
	v_exp_f32_e32 v100, v100
	v_exp_f32_e32 v101, v101
	v_exp_f32_e32 v102, v102
	v_exp_f32_e32 v103, v103
	v_exp_f32_e32 v104, v104
	v_exp_f32_e32 v105, v105
	v_exp_f32_e32 v94, v94
	v_exp_f32_e32 v95, v95
	v_exp_f32_e32 v96, v96
	v_exp_f32_e32 v90, v90
	v_exp_f32_e32 v91, v91
	v_exp_f32_e32 v92, v92
	v_exp_f32_e32 v93, v93
	v_exp_f32_e32 v82, v82
	v_exp_f32_e32 v83, v83
	v_exp_f32_e32 v84, v84
	v_exp_f32_e32 v85, v85
	v_exp_f32_e32 v86, v86
	v_exp_f32_e32 v87, v87
	v_exp_f32_e32 v88, v88
	v_exp_f32_e32 v89, v89
	v_exp_f32_e32 v78, v78
	v_exp_f32_e32 v79, v79
	v_exp_f32_e32 v80, v80
	v_cvt_pk_bf16_f32 v146, v106, v107
	v_cvt_pk_bf16_f32 v147, v108, v109
	v_cvt_pk_bf16_f32 v148, v98, v99
	v_cvt_pk_bf16_f32 v149, v100, v101
	v_cvt_pk_bf16_f32 v150, v102, v103
	v_cvt_pk_bf16_f32 v151, v104, v105
	v_cvt_pk_bf16_f32 v152, v94, v95
	v_cvt_pk_bf16_f32 v153, v96, v97
	v_cvt_pk_bf16_f32 v154, v90, v91
	v_cvt_pk_bf16_f32 v155, v92, v93
	v_cvt_pk_bf16_f32 v156, v82, v83
	v_cvt_pk_bf16_f32 v157, v84, v85
	v_cvt_pk_bf16_f32 v176, v86, v87
	v_cvt_pk_bf16_f32 v177, v88, v89
	v_cvt_pk_bf16_f32 v178, v78, v79
	v_cvt_pk_bf16_f32 v179, v80, v81
	s_setprio 1
	s_waitcnt lgkmcnt(14)
	v_mfma_f32_16x16x32_bf16 v[74:77], v[158:161], v[146:149], v[74:77]
	v_mfma_f32_16x16x32_bf16 v[58:61], v[158:161], v[154:157], v[58:61]
	s_waitcnt lgkmcnt(12)
	v_mfma_f32_16x16x32_bf16 v[54:57], v[164:167], v[146:149], v[54:57]
	v_mfma_f32_16x16x32_bf16 v[158:161], v[164:167], v[154:157], v[70:73]
	s_waitcnt lgkmcnt(10)
	v_mfma_f32_16x16x32_bf16 v[74:77], v[168:171], v[150:153], v[74:77]
	v_mfma_f32_16x16x32_bf16 v[58:61], v[168:171], v[176:179], v[58:61]
	s_waitcnt lgkmcnt(8)
	v_mfma_f32_16x16x32_bf16 v[70:73], v[172:175], v[150:153], v[54:57]
	v_mfma_f32_16x16x32_bf16 v[54:57], v[172:175], v[176:179], v[158:161]
	s_setprio 0
	s_setprio 1
	s_waitcnt lgkmcnt(6)
	v_mfma_f32_16x16x32_bf16 v[50:53], v[224:227], v[146:149], v[50:53]
	v_mfma_f32_16x16x32_bf16 v[158:161], v[224:227], v[154:157], v[66:69]
	s_waitcnt lgkmcnt(4)
	v_mfma_f32_16x16x32_bf16 v[46:49], v[228:231], v[146:149], v[46:49]
	v_mfma_f32_16x16x32_bf16 v[142:145], v[228:231], v[154:157], v[62:65]
	s_waitcnt lgkmcnt(2)
	v_mfma_f32_16x16x32_bf16 v[66:69], v[232:235], v[150:153], v[50:53]
	v_mfma_f32_16x16x32_bf16 v[50:53], v[232:235], v[176:179], v[158:161]
	s_waitcnt lgkmcnt(0)
	v_mfma_f32_16x16x32_bf16 v[62:65], v[236:239], v[150:153], v[46:49]
	v_mfma_f32_16x16x32_bf16 v[46:49], v[236:239], v[176:179], v[142:145]
	s_setprio 0
	s_andn2_b64 vcc, exec, s[2:3]
	s_cbranch_vccnz .LBB0_556
	s_xor_b32 s5, s5, 0x80
	v_add_u32_e32 v144, s5, v126
	v_mad_u64_u32 v[142:143], s[2:3], v144, s12, v[114:115]
	s_waitcnt vmcnt(4)
	ds_write_b128 v142, v[10:13]
	v_mad_u64_u32 v[142:143], s[2:3], v144, s16, v[114:115]
	v_add_u32_e32 v144, s5, v127
	s_waitcnt vmcnt(3)
	ds_write_b128 v142, v[14:17] offset:53248
	v_mad_u64_u32 v[142:143], s[2:3], v144, s12, v[114:115]
	s_waitcnt vmcnt(2)
	ds_write_b128 v142, v[18:21]
	v_mad_u64_u32 v[142:143], s[2:3], v144, s16, v[114:115]
	s_waitcnt vmcnt(1)
	ds_write_b128 v142, v[22:25] offset:53248
	v_add_u32_e32 v142, s5, v128
	v_mad_u64_u32 v[142:143], s[2:3], v142, s12, v[116:117]
	s_waitcnt vmcnt(0)
	ds_write_b128 v142, v[34:37] offset:128
	s_branch .LBB0_556

.LBB0_576:
	s_and_b32 s5, s7, 0x80
	v_or_b32_e32 v142, s5, v125
	v_mad_u32_u24 v143, v142, s12, v0
	ds_read_b128 v[78:81], v143
	ds_read_b128 v[82:85], v143 offset:64
	ds_read_b128 v[86:89], v143 offset:128
	ds_read_b128 v[94:97], v143 offset:3328
	ds_read_b128 v[98:101], v143 offset:3392
	ds_read_b128 v[144:147], v143 offset:3456
	ds_read_b128 v[224:227], v143 offset:6656
	ds_read_b128 v[228:231], v143 offset:6720
	ds_read_b128 v[232:235], v143 offset:6784
	ds_read_b128 v[236:239], v143 offset:9984
	ds_read_b128 v[240:243], v143 offset:10048
	ds_read_b128 v[244:247], v143 offset:10112
	s_setprio 1
	s_waitcnt lgkmcnt(11)
	v_mfma_f32_16x16x32_bf16 v[90:93], v[78:81], v[2:5], 0
	v_mfma_f32_16x16x32_bf16 v[78:81], v[78:81], v[26:29], 0
	s_waitcnt lgkmcnt(10)
	v_mfma_f32_16x16x32_bf16 v[90:93], v[82:85], v[6:9], v[90:93]
	v_mfma_f32_16x16x32_bf16 v[78:81], v[82:85], v[30:33], v[78:81]
	s_waitcnt lgkmcnt(9)
	v_mfma_f32_16x16x32_bf16 v[106:109], v[86:89], v[38:41], v[90:93]
	v_mfma_f32_16x16x32_bf16 v[90:93], v[86:89], v[42:45], v[78:81]
	s_waitcnt lgkmcnt(8)
	v_mfma_f32_16x16x32_bf16 v[78:81], v[94:97], v[2:5], 0
	v_mfma_f32_16x16x32_bf16 v[82:85], v[94:97], v[26:29], 0
	s_waitcnt lgkmcnt(7)
	v_mfma_f32_16x16x32_bf16 v[78:81], v[98:101], v[6:9], v[78:81]
	v_mfma_f32_16x16x32_bf16 v[82:85], v[98:101], v[30:33], v[82:85]
	s_waitcnt lgkmcnt(6)
	v_mfma_f32_16x16x32_bf16 v[102:105], v[144:147], v[38:41], v[78:81]
	v_mfma_f32_16x16x32_bf16 v[82:85], v[144:147], v[42:45], v[82:85]
	s_setprio 0
	s_nop 2
	s_setprio 1
	s_waitcnt lgkmcnt(5)
	v_mfma_f32_16x16x32_bf16 v[98:101], v[224:227], v[2:5], 0
	v_mfma_f32_16x16x32_bf16 v[78:81], v[224:227], v[26:29], 0
	s_waitcnt lgkmcnt(4)
	v_mfma_f32_16x16x32_bf16 v[98:101], v[228:231], v[6:9], v[98:101]
	v_mfma_f32_16x16x32_bf16 v[78:81], v[228:231], v[30:33], v[78:81]
	s_waitcnt lgkmcnt(3)
	v_mfma_f32_16x16x32_bf16 v[98:101], v[232:235], v[38:41], v[98:101]
	v_mfma_f32_16x16x32_bf16 v[86:89], v[232:235], v[42:45], v[78:81]
	s_waitcnt lgkmcnt(2)
	v_mfma_f32_16x16x32_bf16 v[78:81], v[236:239], v[2:5], 0
	v_mfma_f32_16x16x32_bf16 v[94:97], v[236:239], v[26:29], 0
	s_waitcnt lgkmcnt(1)
	v_mfma_f32_16x16x32_bf16 v[78:81], v[240:243], v[6:9], v[78:81]
	v_mfma_f32_16x16x32_bf16 v[144:147], v[240:243], v[30:33], v[94:97]
	s_waitcnt lgkmcnt(0)
	v_mfma_f32_16x16x32_bf16 v[94:97], v[244:247], v[38:41], v[78:81]
	v_mfma_f32_16x16x32_bf16 v[78:81], v[244:247], v[42:45], v[144:147]
	s_setprio 0
	v_max3_f32 v143, v106, s18, v107
	v_max3_f32 v143, v143, v108, v109
	v_max3_f32 v143, v143, v102, v103
	v_max3_f32 v143, v143, v104, v105
	v_max3_f32 v143, v143, v98, v99
	v_max3_f32 v143, v143, v100, v101
	v_max3_f32 v143, v143, v94, v95
	v_max3_f32 v143, v143, v96, v97
	v_mul_f32_e32 v143, 0x3e16c740, v143
	ds_bpermute_b32 v144, v124, v143
	s_waitcnt lgkmcnt(0)
	v_max_f32_e32 v144, v144, v144
	v_max_f32_e32 v143, v143, v144
	ds_bpermute_b32 v144, v127, v143
	s_waitcnt lgkmcnt(0)
	v_max_f32_e32 v144, v144, v144
	v_max_f32_e32 v143, v143, v144
	v_add_f32_e32 v144, 0x41000000, v139
	v_cmp_gt_f32_e32 vcc, v143, v144
	s_cbranch_vccz .LBB0_578
	v_max_f32_e32 v143, v143, v143
	v_max_f32_e32 v144, v139, v139
	v_max_f32_e32 v143, v144, v143
	v_sub_f32_e32 v139, v139, v143
	v_exp_f32_e32 v144, v139
	v_mov_b32_e32 v139, v143
	v_mul_f32_e32 v141, v141, v144
	v_pk_mul_f32 v[76:77], v[76:77], v[144:145] op_sel_hi:[1,0]
	v_pk_mul_f32 v[74:75], v[74:75], v[144:145] op_sel_hi:[1,0]
	v_pk_mul_f32 v[72:73], v[72:73], v[144:145] op_sel_hi:[1,0]
	v_pk_mul_f32 v[70:71], v[70:71], v[144:145] op_sel_hi:[1,0]
	v_pk_mul_f32 v[68:69], v[68:69], v[144:145] op_sel_hi:[1,0]
	v_pk_mul_f32 v[66:67], v[66:67], v[144:145] op_sel_hi:[1,0]
	v_pk_mul_f32 v[64:65], v[64:65], v[144:145] op_sel_hi:[1,0]
	v_pk_mul_f32 v[62:63], v[62:63], v[144:145] op_sel_hi:[1,0]

.LBB0_580:
	v_fma_f32 v106, v106, s21, -v139
	v_exp_f32_e32 v106, v106
	v_fma_f32 v107, v107, s21, -v139
	v_exp_f32_e32 v107, v107
	v_fma_f32 v108, v108, s21, -v139
	v_exp_f32_e32 v108, v108
	v_fma_f32 v109, v109, s21, -v139
	v_exp_f32_e32 v109, v109
	v_fma_f32 v102, v102, s21, -v139
	v_mul_u32_u24_e32 v160, 0xd0, v142
	v_add_f32_e32 v142, 0, v106
	v_exp_f32_e32 v102, v102
	v_fma_f32 v103, v103, s21, -v139
	v_add_f32_e32 v142, v107, v142
	v_exp_f32_e32 v103, v103
	v_fma_f32 v104, v104, s21, -v139
	v_add_f32_e32 v142, v108, v142
	v_exp_f32_e32 v104, v104
	v_fma_f32 v105, v105, s21, -v139
	v_add_f32_e32 v142, v109, v142
	v_exp_f32_e32 v105, v105
	v_fma_f32 v98, v98, s21, -v139
	v_cvt_pk_bf16_f32 v106, v106, v107
	v_cvt_pk_bf16_f32 v107, v108, v109
	v_add_f32_e32 v108, v102, v142
	v_exp_f32_e32 v98, v98
	v_fma_f32 v99, v99, s21, -v139
	v_add_f32_e32 v108, v103, v108
	v_exp_f32_e32 v99, v99
	v_fma_f32 v100, v100, s21, -v139
	v_add_f32_e32 v108, v104, v108
	v_exp_f32_e32 v100, v100
	v_fma_f32 v101, v101, s21, -v139
	v_add_f32_e32 v142, v105, v108
	v_exp_f32_e32 v101, v101
	v_fma_f32 v94, v94, s21, -v139
	v_cvt_pk_bf16_f32 v108, v102, v103
	v_add_f32_e32 v102, v98, v142
	v_exp_f32_e32 v94, v94
	v_fma_f32 v95, v95, s21, -v139
	v_add_f32_e32 v102, v99, v102
	v_exp_f32_e32 v95, v95
	v_fma_f32 v96, v96, s21, -v139
	v_add_f32_e32 v102, v100, v102
	v_exp_f32_e32 v96, v96
	v_fma_f32 v97, v97, s21, -v139
	v_add_f32_e32 v102, v101, v102
	v_exp_f32_e32 v97, v97
	v_cvt_pk_bf16_f32 v98, v98, v99
	v_cvt_pk_bf16_f32 v99, v100, v101
	v_add_f32_e32 v100, v94, v102
	v_add_f32_e32 v100, v95, v100
	v_add_f32_e32 v100, v96, v100
	v_fma_f32 v90, v90, s21, -v138
	v_fma_f32 v86, v86, s21, -v138
	v_fma_f32 v78, v78, s21, -v138
	v_add_f32_e32 v102, v97, v100
	v_cvt_pk_bf16_f32 v100, v94, v95
	v_or_b32_e32 v94, s5, v132
	v_exp_f32_e32 v144, v90
	v_fma_f32 v90, v91, s21, -v138
	v_exp_f32_e32 v159, v86
	v_fma_f32 v86, v87, s21, -v138
	v_exp_f32_e32 v154, v78
	v_fma_f32 v78, v79, s21, -v138
	v_exp_f32_e32 v145, v90
	v_fma_f32 v90, v92, s21, -v138
	v_exp_f32_e32 v146, v86
	v_fma_f32 v86, v88, s21, -v138
	v_exp_f32_e32 v151, v78
	v_fma_f32 v78, v80, s21, -v138
	v_mul_u32_u24_e32 v143, 0x48, v94
	v_exp_f32_e32 v147, v90
	v_fma_f32 v90, v93, s21, -v138
	v_exp_f32_e32 v148, v86
	v_fma_f32 v86, v89, s21, -v138
	v_exp_f32_e32 v152, v78
	v_fma_f32 v78, v81, s21, -v138
	v_lshl_add_u32 v142, v143, 1, v130
	v_cvt_pk_bf16_f32 v101, v96, v97
	v_exp_f32_e32 v149, v90
	v_exp_f32_e32 v150, v86
	v_exp_f32_e32 v155, v78
	ds_read_b64_tr_b16 v[80:81], v142 offset:55552
	ds_read_b64_tr_b16 v[78:79], v142 offset:53248
	ds_read_b64_tr_b16 v[88:89], v142 offset:55584
	ds_read_b64_tr_b16 v[86:87], v142 offset:53280
	ds_read_b64_tr_b16 v[90:91], v142 offset:57856
	ds_read_b64_tr_b16 v[92:93], v142 offset:60160
	ds_read_b64_tr_b16 v[96:97], v142 offset:60192
	ds_read_b64_tr_b16 v[94:95], v142 offset:57888
	ds_read_b64_tr_b16 v[226:227], v142 offset:55616
	ds_read_b64_tr_b16 v[224:225], v142 offset:53312
	ds_read_b64_tr_b16 v[230:231], v142 offset:55648
	ds_read_b64_tr_b16 v[228:229], v142 offset:53344
	ds_read_b64_tr_b16 v[232:233], v142 offset:57920
	ds_read_b64_tr_b16 v[234:235], v142 offset:60224
	ds_read_b64_tr_b16 v[238:239], v142 offset:60256
	ds_read_b64_tr_b16 v[236:237], v142 offset:57952
	v_fma_f32 v82, v82, s21, -v138
	v_exp_f32_e32 v153, v82
	v_fma_f32 v82, v83, s21, -v138
	v_exp_f32_e32 v156, v82
	v_fma_f32 v82, v84, s21, -v138
	v_exp_f32_e32 v157, v82
	v_fma_f32 v82, v85, s21, -v138
	v_exp_f32_e32 v158, v82
	v_cvt_pk_bf16_f32 v109, v104, v105
	v_add_f32_e32 v141, v141, v102
	v_cvt_pk_bf16_f32 v82, v144, v145
	v_cvt_pk_bf16_f32 v83, v147, v149
	v_cvt_pk_bf16_f32 v84, v153, v156
	v_cvt_pk_bf16_f32 v85, v157, v158
	v_cvt_pk_bf16_f32 v102, v159, v146
	v_cvt_pk_bf16_f32 v103, v148, v150
	v_cvt_pk_bf16_f32 v104, v154, v151
	v_cvt_pk_bf16_f32 v105, v152, v155
	s_setprio 1
	s_waitcnt lgkmcnt(14)
	v_mfma_f32_16x16x32_bf16 v[74:77], v[78:81], v[106:109], v[74:77]
	v_mfma_f32_16x16x32_bf16 v[58:61], v[78:81], v[82:85], v[58:61]
	s_waitcnt lgkmcnt(12)
	v_mfma_f32_16x16x32_bf16 v[70:73], v[86:89], v[106:109], v[70:73]
	v_mfma_f32_16x16x32_bf16 v[78:81], v[86:89], v[82:85], v[54:57]
	s_waitcnt lgkmcnt(10)
	v_mfma_f32_16x16x32_bf16 v[74:77], v[90:93], v[98:101], v[74:77]
	v_mfma_f32_16x16x32_bf16 v[58:61], v[90:93], v[102:105], v[58:61]
	s_waitcnt lgkmcnt(8)
	v_mfma_f32_16x16x32_bf16 v[54:57], v[94:97], v[98:101], v[70:73]
	v_mfma_f32_16x16x32_bf16 v[70:73], v[94:97], v[102:105], v[78:81]
	s_setprio 0
	s_nop 1
	v_add_u32_e32 v160, v0, v160
	ds_read_b128 v[240:243], v160 offset:13312
	ds_read_b128 v[244:247], v160 offset:13376
	ds_read_b128 v[86:89], v160 offset:13440
	ds_read_b128 v[94:97], v160 offset:16640
	ds_read_b128 v[200:203], v160 offset:16704
	ds_read_b128 v[182:185], v160 offset:16768
	s_setprio 1
	s_waitcnt lgkmcnt(12)
	v_mfma_f32_16x16x32_bf16 v[66:69], v[224:227], v[106:109], v[66:69]
	v_mfma_f32_16x16x32_bf16 v[78:81], v[224:227], v[82:85], v[50:53]
	s_waitcnt lgkmcnt(8)
	v_mfma_f32_16x16x32_bf16 v[50:53], v[232:235], v[98:101], v[66:69]
	v_mfma_f32_16x16x32_bf16 v[66:69], v[232:235], v[102:105], v[78:81]
	v_mfma_f32_16x16x32_bf16 v[62:65], v[228:231], v[106:109], v[62:65]
	v_mfma_f32_16x16x32_bf16 v[78:81], v[228:231], v[82:85], v[46:49]
	s_waitcnt lgkmcnt(6)
	v_mfma_f32_16x16x32_bf16 v[46:49], v[236:239], v[98:101], v[62:65]
	v_mfma_f32_16x16x32_bf16 v[62:65], v[236:239], v[102:105], v[78:81]
	s_setprio 0
	s_nop 2
	ds_read_b128 v[224:227], v160 offset:19968
	ds_read_b128 v[228:231], v160 offset:20032
	ds_read_b128 v[232:235], v160 offset:20096
	ds_read_b128 v[164:167], v160 offset:23296
	ds_read_b128 v[168:171], v160 offset:23360
	ds_read_b128 v[172:175], v160 offset:23424
	s_setprio 1
	s_waitcnt lgkmcnt(11)
	v_mfma_f32_16x16x32_bf16 v[90:93], v[240:243], v[2:5], 0
	v_mfma_f32_16x16x32_bf16 v[78:81], v[240:243], v[26:29], 0
	s_waitcnt lgkmcnt(10)
	v_mfma_f32_16x16x32_bf16 v[90:93], v[244:247], v[6:9], v[90:93]
	v_mfma_f32_16x16x32_bf16 v[78:81], v[244:247], v[30:33], v[78:81]
	s_waitcnt lgkmcnt(9)
	v_mfma_f32_16x16x32_bf16 v[106:109], v[86:89], v[38:41], v[90:93]
	v_mfma_f32_16x16x32_bf16 v[90:93], v[86:89], v[42:45], v[78:81]
	s_waitcnt lgkmcnt(8)
	v_mfma_f32_16x16x32_bf16 v[78:81], v[94:97], v[2:5], 0
	v_mfma_f32_16x16x32_bf16 v[82:85], v[94:97], v[26:29], 0
	s_waitcnt lgkmcnt(7)
	v_mfma_f32_16x16x32_bf16 v[78:81], v[200:203], v[6:9], v[78:81]
	v_mfma_f32_16x16x32_bf16 v[82:85], v[200:203], v[30:33], v[82:85]
	s_waitcnt lgkmcnt(6)
	v_mfma_f32_16x16x32_bf16 v[98:101], v[182:185], v[38:41], v[78:81]
	v_mfma_f32_16x16x32_bf16 v[82:85], v[182:185], v[42:45], v[82:85]
	s_setprio 0
	s_nop 2
	s_setprio 1
	s_waitcnt lgkmcnt(5)
	v_mfma_f32_16x16x32_bf16 v[102:105], v[224:227], v[2:5], 0
	v_mfma_f32_16x16x32_bf16 v[78:81], v[224:227], v[26:29], 0
	s_waitcnt lgkmcnt(4)
	v_mfma_f32_16x16x32_bf16 v[102:105], v[228:231], v[6:9], v[102:105]
	v_mfma_f32_16x16x32_bf16 v[78:81], v[228:231], v[30:33], v[78:81]
	s_waitcnt lgkmcnt(3)
	v_mfma_f32_16x16x32_bf16 v[102:105], v[232:235], v[38:41], v[102:105]
	v_mfma_f32_16x16x32_bf16 v[86:89], v[232:235], v[42:45], v[78:81]
	s_waitcnt lgkmcnt(2)
	v_mfma_f32_16x16x32_bf16 v[78:81], v[164:167], v[2:5], 0
	v_mfma_f32_16x16x32_bf16 v[94:97], v[164:167], v[26:29], 0
	s_waitcnt lgkmcnt(1)
	v_mfma_f32_16x16x32_bf16 v[78:81], v[168:171], v[6:9], v[78:81]
	v_mfma_f32_16x16x32_bf16 v[164:167], v[168:171], v[30:33], v[94:97]
	s_waitcnt lgkmcnt(0)
	v_mfma_f32_16x16x32_bf16 v[94:97], v[172:175], v[38:41], v[78:81]
	v_mfma_f32_16x16x32_bf16 v[78:81], v[172:175], v[42:45], v[164:167]
	s_setprio 0
	v_max3_f32 v160, v106, s18, v107
	v_max3_f32 v160, v160, v108, v109
	v_max3_f32 v160, v160, v98, v99
	v_max3_f32 v160, v160, v100, v101
	v_max3_f32 v160, v160, v102, v103
	v_max3_f32 v160, v160, v104, v105
	v_max3_f32 v160, v160, v94, v95
	v_max3_f32 v160, v160, v96, v97
	v_mul_f32_e32 v160, 0x3e16c740, v160
	ds_bpermute_b32 v161, v124, v160
	s_waitcnt lgkmcnt(0)
	v_max_f32_e32 v161, v161, v161
	v_max_f32_e32 v160, v160, v161
	ds_bpermute_b32 v161, v127, v160
	s_waitcnt lgkmcnt(0)
	v_max_f32_e32 v161, v161, v161
	v_max_f32_e32 v160, v160, v161
	v_add_f32_e32 v161, 0x41000000, v139
	v_cmp_gt_f32_e32 vcc, v160, v161
	s_cbranch_vccz .LBB0_582
	v_max_f32_e32 v160, v160, v160
	v_max_f32_e32 v161, v139, v139
	v_max_f32_e32 v161, v161, v160
	v_sub_f32_e32 v139, v139, v161
	v_exp_f32_e32 v160, v139
	v_mov_b32_e32 v139, v161
	v_mul_f32_e32 v141, v141, v160
	v_pk_mul_f32 v[76:77], v[76:77], v[160:161] op_sel_hi:[1,0]
	v_pk_mul_f32 v[74:75], v[74:75], v[160:161] op_sel_hi:[1,0]
	v_pk_mul_f32 v[56:57], v[56:57], v[160:161] op_sel_hi:[1,0]
	v_pk_mul_f32 v[54:55], v[54:55], v[160:161] op_sel_hi:[1,0]
	v_pk_mul_f32 v[52:53], v[52:53], v[160:161] op_sel_hi:[1,0]
	v_pk_mul_f32 v[50:51], v[50:51], v[160:161] op_sel_hi:[1,0]
	v_pk_mul_f32 v[48:49], v[48:49], v[160:161] op_sel_hi:[1,0]
	v_pk_mul_f32 v[46:47], v[46:47], v[160:161] op_sel_hi:[1,0]
	v_xor_b32_e32 v160, 0x80000000, v161
	s_branch .LBB0_583

.LBB0_586:
	v_lshl_add_u32 v180, v143, 1, v210
	v_fmamk_f32 v106, v106, 0x3e16c740, v160
	v_fmamk_f32 v107, v107, 0x3e16c740, v160
	v_fmamk_f32 v108, v108, 0x3e16c740, v160
	v_fmamk_f32 v109, v109, 0x3e16c740, v160
	v_fmamk_f32 v98, v98, 0x3e16c740, v160
	v_fmamk_f32 v99, v99, 0x3e16c740, v160
	v_fmamk_f32 v100, v100, 0x3e16c740, v160
	v_fmamk_f32 v101, v101, 0x3e16c740, v160
	v_fmamk_f32 v102, v102, 0x3e16c740, v160
	v_fmamk_f32 v103, v103, 0x3e16c740, v160
	v_fmamk_f32 v104, v104, 0x3e16c740, v160
	v_fmamk_f32 v105, v105, 0x3e16c740, v160
	v_fmamk_f32 v94, v94, 0x3e16c740, v160
	v_fmamk_f32 v95, v95, 0x3e16c740, v160
	v_fmamk_f32 v96, v96, 0x3e16c740, v160
	v_fmac_f32_e32 v160, 0x3e16c740, v97
	v_fmamk_f32 v90, v90, 0x3e16c740, v144
	v_fmamk_f32 v91, v91, 0x3e16c740, v144
	v_fmamk_f32 v92, v92, 0x3e16c740, v144
	v_fmamk_f32 v93, v93, 0x3e16c740, v144
	v_fmamk_f32 v82, v82, 0x3e16c740, v144
	v_fmamk_f32 v83, v83, 0x3e16c740, v144
	v_fmamk_f32 v84, v84, 0x3e16c740, v144
	v_fmamk_f32 v85, v85, 0x3e16c740, v144
	v_fmamk_f32 v86, v86, 0x3e16c740, v144
	v_fmamk_f32 v87, v87, 0x3e16c740, v144
	v_fmamk_f32 v88, v88, 0x3e16c740, v144
	v_fmamk_f32 v89, v89, 0x3e16c740, v144
	v_fmamk_f32 v78, v78, 0x3e16c740, v144
	v_fmamk_f32 v79, v79, 0x3e16c740, v144
	v_fmamk_f32 v80, v80, 0x3e16c740, v144
	v_fmac_f32_e32 v144, 0x3e16c740, v81
	v_add_u32_e32 v143, v133, v180
	v_exp_f32_e32 v97, v160
	v_exp_f32_e32 v81, v144
	ds_read_b64_tr_b16 v[160:161], v142 offset:64768
	ds_read_b64_tr_b16 v[158:159], v142 offset:62464
	ds_read_b64_tr_b16 v[166:167], v142 offset:64800
	ds_read_b64_tr_b16 v[164:165], v142 offset:62496
	v_add_u32_e32 v144, v134, v180
	ds_read_b64_tr_b16 v[168:169], v143
	ds_read_b64_tr_b16 v[170:171], v143 offset:2304
	ds_read_b64_tr_b16 v[172:173], v144
	ds_read_b64_tr_b16 v[174:175], v144 offset:2304
	v_add_u32_e32 v186, v135, v180
	v_add_u32_e32 v187, v136, v180
	ds_read_b64_tr_b16 v[226:227], v142 offset:64832
	ds_read_b64_tr_b16 v[224:225], v142 offset:62528
	ds_read_b64_tr_b16 v[230:231], v142 offset:64864
	ds_read_b64_tr_b16 v[228:229], v142 offset:62560
	ds_read_b64_tr_b16 v[232:233], v186
	ds_read_b64_tr_b16 v[234:235], v186 offset:2304
	ds_read_b64_tr_b16 v[236:237], v187
	ds_read_b64_tr_b16 v[238:239], v187 offset:2304
	v_exp_f32_e32 v106, v106
	v_exp_f32_e32 v107, v107
	v_exp_f32_e32 v108, v108
	v_exp_f32_e32 v109, v109
	v_exp_f32_e32 v98, v98
	v_exp_f32_e32 v99, v99
	v_exp_f32_e32 v100, v100
	v_exp_f32_e32 v101, v101
	v_exp_f32_e32 v102, v102
	v_exp_f32_e32 v103, v103
	v_exp_f32_e32 v104, v104
	v_exp_f32_e32 v105, v105
	v_exp_f32_e32 v94, v94
	v_exp_f32_e32 v95, v95
	v_exp_f32_e32 v96, v96
	v_exp_f32_e32 v90, v90
	v_exp_f32_e32 v91, v91
	v_exp_f32_e32 v92, v92
	v_exp_f32_e32 v93, v93
	v_exp_f32_e32 v82, v82
	v_exp_f32_e32 v83, v83
	v_exp_f32_e32 v84, v84
	v_exp_f32_e32 v85, v85
	v_exp_f32_e32 v86, v86
	v_exp_f32_e32 v87, v87
	v_exp_f32_e32 v88, v88
	v_exp_f32_e32 v89, v89
	v_exp_f32_e32 v78, v78
	v_exp_f32_e32 v79, v79
	v_exp_f32_e32 v80, v80
	v_cvt_pk_bf16_f32 v146, v106, v107
	v_cvt_pk_bf16_f32 v147, v108, v109
	v_cvt_pk_bf16_f32 v148, v98, v99
	v_cvt_pk_bf16_f32 v149, v100, v101
	v_cvt_pk_bf16_f32 v150, v102, v103
	v_cvt_pk_bf16_f32 v151, v104, v105
	v_cvt_pk_bf16_f32 v152, v94, v95
	v_cvt_pk_bf16_f32 v153, v96, v97
	v_cvt_pk_bf16_f32 v154, v90, v91
	v_cvt_pk_bf16_f32 v155, v92, v93
	v_cvt_pk_bf16_f32 v156, v82, v83
	v_cvt_pk_bf16_f32 v157, v84, v85
	v_cvt_pk_bf16_f32 v176, v86, v87
	v_cvt_pk_bf16_f32 v177, v88, v89
	v_cvt_pk_bf16_f32 v178, v78, v79
	v_cvt_pk_bf16_f32 v179, v80, v81
	s_setprio 1
	s_waitcnt lgkmcnt(14)
	v_mfma_f32_16x16x32_bf16 v[74:77], v[158:161], v[146:149], v[74:77]
	v_mfma_f32_16x16x32_bf16 v[58:61], v[158:161], v[154:157], v[58:61]
	s_waitcnt lgkmcnt(12)
	v_mfma_f32_16x16x32_bf16 v[54:57], v[164:167], v[146:149], v[54:57]
	v_mfma_f32_16x16x32_bf16 v[158:161], v[164:167], v[154:157], v[70:73]
	s_waitcnt lgkmcnt(10)
	v_mfma_f32_16x16x32_bf16 v[74:77], v[168:171], v[150:153], v[74:77]
	v_mfma_f32_16x16x32_bf16 v[58:61], v[168:171], v[176:179], v[58:61]
	s_waitcnt lgkmcnt(8)
	v_mfma_f32_16x16x32_bf16 v[70:73], v[172:175], v[150:153], v[54:57]
	v_mfma_f32_16x16x32_bf16 v[54:57], v[172:175], v[176:179], v[158:161]
	s_setprio 0
	s_setprio 1
	s_waitcnt lgkmcnt(6)
	v_mfma_f32_16x16x32_bf16 v[50:53], v[224:227], v[146:149], v[50:53]
	v_mfma_f32_16x16x32_bf16 v[158:161], v[224:227], v[154:157], v[66:69]
	s_waitcnt lgkmcnt(4)
	v_mfma_f32_16x16x32_bf16 v[46:49], v[228:231], v[146:149], v[46:49]
	v_mfma_f32_16x16x32_bf16 v[142:145], v[228:231], v[154:157], v[62:65]
	s_waitcnt lgkmcnt(2)
	v_mfma_f32_16x16x32_bf16 v[66:69], v[232:235], v[150:153], v[50:53]
	v_mfma_f32_16x16x32_bf16 v[50:53], v[232:235], v[176:179], v[158:161]
	s_waitcnt lgkmcnt(0)
	v_mfma_f32_16x16x32_bf16 v[62:65], v[236:239], v[150:153], v[46:49]
	v_mfma_f32_16x16x32_bf16 v[46:49], v[236:239], v[176:179], v[142:145]
	s_setprio 0
	s_andn2_b64 vcc, exec, s[2:3]
	s_cbranch_vccnz .LBB0_573
	s_xor_b32 s5, s5, 0x80
	v_add_u32_e32 v144, s5, v126
	v_mad_u64_u32 v[142:143], s[2:3], v144, s12, v[114:115]
	s_waitcnt vmcnt(4)
	ds_write_b128 v142, v[10:13]
	v_mad_u64_u32 v[142:143], s[2:3], v144, s16, v[114:115]
	v_add_u32_e32 v144, s5, v128
	s_waitcnt vmcnt(3)
	ds_write_b128 v142, v[14:17] offset:53248
	v_mad_u64_u32 v[142:143], s[2:3], v144, s12, v[114:115]
	s_waitcnt vmcnt(2)
	ds_write_b128 v142, v[18:21]
	v_mad_u64_u32 v[142:143], s[2:3], v144, s16, v[114:115]
	s_waitcnt vmcnt(1)
	ds_write_b128 v142, v[22:25] offset:53248
	v_add_u32_e32 v142, s5, v129
	v_mad_u64_u32 v[142:143], s[2:3], v142, s12, v[116:117]
	s_waitcnt vmcnt(0)
	ds_write_b128 v142, v[34:37] offset:128
	s_branch .LBB0_573
